# stack17 + RMSNorm phases: wave index relabelled so the ninth row round is spread over all workgroups; norm1 extra-panel rows: eight loads issued together instead of eight serial round trips
# speedup vs baseline: 1.0077x; 1.0040x over previous
; #define GAS __attribute__((address_space(1)))
; __device__ __forceinline__ unsigned pk2(float lo, float hi) { return pg8::cvt_pk_bf16(lo, hi); }
; #define INP(k) (*(const float* const __attribute__((address_space(4)))*)(ka + 8 * (k)))
; __device__ __forceinline__ int launder_si(int v) { asm volatile("" : "+s"(v)); return v; }
; __device__ __forceinline__ void phase_norm(Frame& F, int l, int mode) {
;     ...
;     const int gw = launder_si(F.vcu * NWAVES + F.wave), NGW = F.G * NWAVES;
;     GAS bf16* XB = (GAS bf16*)out_; GAS bf16* XS = (GAS bf16*)(ws_ + WS_RKV); GAS bf16* HB = (GAS bf16*)(ws_ + WS_HB);
;     const float* gain = (mode == 0) ? INP(5) + (size_t)l * D : (mode == 1) ? INP(22) + (size_t)l * D : INP(25);
;     if (mode == 0 && gw < BS) {
;         const int j = gw; GAS v2u* o8 = (GAS v2u*)(HB + (size_t)(M + j) * D) + lane;
; #pragma unroll
;         for (int q = 0; q < 8; ++q) { const f32x4 s = *((const GAS f32x4*)(INP(3) + ((size_t)l * BS + j) * D) + lane + 64 * q); v2u w; w.x = pk2(s.x, s.y); w.y = pk2(s.z, s.w); o8[64 * q] = w; }
;     }
.LBB0_178:
	s_andn2_b64 vcc, exec, s[6:7]
	s_cbranch_vccnz .LBB0_256
	v_readlane_b32 s0, v254, 0
	v_readlane_b32 s1, v254, 1
	s_waitcnt lgkmcnt(0)
	s_load_dwordx4 s[8:11], s[0:1], 0xd0
	s_mov_b32 s18, s91
	s_mov_b64 s[6:7], s[0:1]
	s_waitcnt lgkmcnt(0)
	s_mov_b64 s[14:15], s[10:11]
	s_mov_b64 s[26:27], s[8:9]
	v_readlane_b32 s8, v254, 12
	s_and_b32 s98, s8, 7
	s_lshl_b32 s98, s98, 8
	s_lshr_b32 s8, s8, 3
	s_add_i32 s8, s8, s98
	v_mbcnt_lo_u32_b32 v2, -1, 0
	v_mbcnt_hi_u32_b32 v2, -1, v2
	s_load_dwordx2 s[10:11], s[6:7], 0x28
	s_add_u32 s0, s14, 0x1eb00000
	s_addc_u32 s1, s15, 0
	s_ashr_i32 s19, s18, 31
	s_cmp_gt_i32 s8, 15
	v_readlane_b32 s9, v254, 13
	s_cbranch_scc1 .LBB0_181
	s_load_dwordx2 s[16:17], s[6:7], 0x18
	s_ashr_i32 s9, s8, 31
	s_lshl_b64 s[12:13], s[8:9], 12
	s_add_u32 s12, s0, s12
	s_addc_u32 s13, s1, s13
	s_lshl_b64 s[20:21], s[18:19], 17
	s_waitcnt lgkmcnt(0)
	s_add_u32 s20, s16, s20
	s_addc_u32 s21, s17, s21
	s_lshl_b64 s[16:17], s[8:9], 13
	s_add_u32 s16, s20, s16
	v_ashrrev_i32_e32 v3, 31, v2
	s_addc_u32 s17, s21, s17
	v_lshl_add_u64 v[8:9], v[2:3], 4, s[16:17]
	global_load_dwordx4 v[14:17], v[8:9], off
	global_load_dwordx4 v[18:21], v[8:9], off offset:1024
	global_load_dwordx4 v[22:25], v[8:9], off offset:2048
	global_load_dwordx4 v[26:29], v[8:9], off offset:3072
	v_lshl_add_u64 v[10:11], v[2:3], 3, s[12:13]
	s_mov_b32 s9, 0x4400000
	v_add_co_u32_e32 v12, vcc, s9, v10
	s_mov_b64 s[12:13], 0x4400000
	s_nop 0
	v_addc_co_u32_e32 v13, vcc, 0, v11, vcc
	v_lshl_add_u64 v[10:11], v[10:11], 0, s[12:13]
	v_add_co_u32_e32 v8, vcc, s40, v8
	s_nop 1
	v_addc_co_u32_e32 v9, vcc, 0, v9, vcc
	global_load_dwordx4 v[30:33], v[8:9], off
	global_load_dwordx4 v[34:37], v[8:9], off offset:1024
	global_load_dwordx4 v[38:41], v[8:9], off offset:2048
	global_load_dwordx4 v[42:45], v[8:9], off offset:3072
	s_waitcnt vmcnt(7)
	v_cvt_pk_bf16_f32 v4, v14, v15
	v_cvt_pk_bf16_f32 v5, v16, v17
	global_store_dwordx2 v[12:13], v[4:5], off
	s_waitcnt vmcnt(7)
	v_cvt_pk_bf16_f32 v4, v18, v19
	v_cvt_pk_bf16_f32 v5, v20, v21
	global_store_dwordx2 v[10:11], v[4:5], off offset:512
	s_waitcnt vmcnt(7)
	v_cvt_pk_bf16_f32 v4, v22, v23
	v_cvt_pk_bf16_f32 v5, v24, v25
	global_store_dwordx2 v[10:11], v[4:5], off offset:1024
	s_waitcnt vmcnt(7)
	v_cvt_pk_bf16_f32 v4, v26, v27
	v_cvt_pk_bf16_f32 v5, v28, v29
	global_store_dwordx2 v[10:11], v[4:5], off offset:1536
	s_waitcnt vmcnt(7)
	v_cvt_pk_bf16_f32 v4, v30, v31
	v_cvt_pk_bf16_f32 v5, v32, v33
	global_store_dwordx2 v[10:11], v[4:5], off offset:2048
	s_waitcnt vmcnt(7)
	v_cvt_pk_bf16_f32 v4, v34, v35
	v_cvt_pk_bf16_f32 v5, v36, v37
	global_store_dwordx2 v[10:11], v[4:5], off offset:2560
	s_waitcnt vmcnt(7)
	v_cvt_pk_bf16_f32 v4, v38, v39
	v_cvt_pk_bf16_f32 v5, v40, v41
	global_store_dwordx2 v[10:11], v[4:5], off offset:3072
	s_waitcnt vmcnt(7)
	v_cvt_pk_bf16_f32 v4, v42, v43
	v_cvt_pk_bf16_f32 v5, v44, v45
	global_store_dwordx2 v[10:11], v[4:5], off offset:3584

; #define GAS __attribute__((address_space(1)))
; __device__ __forceinline__ unsigned pk2(float lo, float hi) { return pg8::cvt_pk_bf16(lo, hi); }
; #define INP(k) (*(const float* const __attribute__((address_space(4)))*)(ka + 8 * (k)))
; __device__ __forceinline__ int launder_si(int v) { asm volatile("" : "+s"(v)); return v; }
; __device__ __forceinline__ void phase_norm(Frame& F, int l, int mode) {
;     ...
;     const int gw = launder_si(F.vcu * NWAVES + F.wave), NGW = F.G * NWAVES;
;     GAS bf16* XB = (GAS bf16*)out_; GAS bf16* XS = (GAS bf16*)(ws_ + WS_RKV); GAS bf16* HB = (GAS bf16*)(ws_ + WS_HB);
;     const float* gain = (mode == 0) ? INP(5) + (size_t)l * D : (mode == 1) ? INP(22) + (size_t)l * D : INP(25);
;     if (mode == 0 && gw < BS) {
;         const int j = gw; GAS v2u* o8 = (GAS v2u*)(HB + (size_t)(M + j) * D) + lane;
; #pragma unroll
;         for (int q = 0; q < 8; ++q) { const f32x4 s = *((const GAS f32x4*)(INP(3) + ((size_t)l * BS + j) * D) + lane + 64 * q); v2u w; w.x = pk2(s.x, s.y); w.y = pk2(s.z, s.w); o8[64 * q] = w; }
;     }
;     f32x4 g[4][2];
; #pragma unroll
;     for (int q = 0; q < 4; ++q) { const GAS f32x4* gp = (const GAS f32x4*)(gain + q * 512 + lane * 8); g[q][0] = gp[0]; g[q][1] = gp[1]; }
;     const bool from_in = (mode == 0 && l == 0);
;     const GAS bf16* XR = (mode == 2) ? XS : XB;
;     GAS bf16* XW = (mode == 1 && l == NL - 1) ? XS : XB;
;     f32x4 nf[4][2]; v4u nb[4];
;     ...
;     if (gw < M) NORM_LOAD(gw);
.LBB0_1083:
	s_andn2_b64 vcc, exec, s[8:9]
	s_cbranch_vccnz .LBB0_1141
	v_readlane_b32 s0, v254, 0
	v_readlane_b32 s1, v254, 1
	s_mov_b32 s16, s91
	s_mov_b64 s[18:19], s[0:1]
	s_waitcnt lgkmcnt(0)
	s_load_dwordx4 s[8:11], s[0:1], 0xd0
	v_readlane_b32 s14, v254, 12
	s_and_b32 s98, s14, 7
	s_lshl_b32 s98, s98, 8
	s_lshr_b32 s14, s14, 3
	s_add_i32 s14, s14, s98
	v_mbcnt_lo_u32_b32 v0, -1, 0
	v_mbcnt_hi_u32_b32 v0, -1, v0
	s_waitcnt lgkmcnt(0)
	s_cmpk_gt_i32 s14, 0x43ff
	v_readlane_b32 s15, v254, 13
	s_cbranch_scc1 .LBB0_1093
	s_ashr_i32 s15, s14, 31
	s_lshl_b64 s[12:13], s[14:15], 12
	v_lshlrev_b32_e32 v2, 3, v0
	s_add_u32 s0, s8, s12
	v_ashrrev_i32_e32 v3, 31, v2
	s_addc_u32 s1, s9, s13
	v_lshlrev_b64 v[114:115], 1, v[2:3]
	v_lshl_add_u64 v[26:27], s[0:1], 0, v[114:115]
	s_add_u32 s15, s10, 0x3d5a0000
	s_load_dwordx2 s[0:1], s[18:19], 0xb0
	s_addc_u32 s17, s11, 0
	s_cmp_eq_u32 s16, 3
	s_cselect_b32 s19, s17, s9
	s_cselect_b32 s18, s15, s8
	s_ashr_i32 s17, s16, 31
	s_lshl_b64 s[16:17], s[16:17], 13
	s_waitcnt lgkmcnt(0)
	s_add_u32 s0, s0, s16
	s_addc_u32 s1, s1, s17
	v_lshl_add_u64 v[30:31], v[2:3], 2, s[0:1]
	s_mov_b64 s[0:1], 0x1800
	v_lshl_add_u64 v[2:3], v[30:31], 0, s[0:1]
	v_add_co_u32_e32 v10, vcc, s40, v30
	s_mov_b64 s[0:1], 0x1000
	s_nop 0
	v_addc_co_u32_e32 v11, vcc, 0, v31, vcc
	v_lshl_add_u64 v[14:15], v[30:31], 0, s[0:1]
	global_load_dwordx4 v[2:5], v[2:3], off offset:16
	s_nop 0
	global_load_dwordx4 v[6:9], v[10:11], off
	s_nop 0
	global_load_dwordx4 v[10:13], v[10:11], off offset:2048
	s_nop 0
	global_load_dwordx4 v[14:17], v[14:15], off offset:16
	s_nop 0
	global_load_dwordx4 v[18:21], v[30:31], off offset:2064
	global_load_dwordx4 v[22:25], v[30:31], off offset:2048
	global_load_dwordx4 v[54:57], v[26:27], off offset:2048
	global_load_dwordx4 v[50:53], v[26:27], off offset:3072
	global_load_dwordx4 v[62:65], v[26:27], off
	global_load_dwordx4 v[58:61], v[26:27], off offset:1024
	s_nop 0
	global_load_dwordx4 v[26:29], v[30:31], off offset:16
	s_nop 0
	global_load_dwordx4 v[30:33], v[30:31], off
	v_lshl_add_u64 v[34:35], s[10:11], 0, v[114:115]
	s_mov_b64 s[0:1], 0x43ba0000
	v_lshl_add_u64 v[116:117], v[34:35], 0, s[0:1]
	s_add_i32 s0, s44, s14
	s_ashr_i32 s1, s0, 31
	s_lshl_b64 s[0:1], s[0:1], 12
	s_add_u32 s8, s8, s0
	s_addc_u32 s9, s9, s1
	s_add_u32 s0, s10, s12
	s_addc_u32 s1, s11, s13
	s_add_u32 s10, s0, 0x1eb00000
	v_lshl_add_u64 v[118:119], s[18:19], 0, v[114:115]
	s_addc_u32 s11, s1, 0
	s_waitcnt vmcnt(0)
	v_mov_b64_e32 v[38:39], v[54:55]
	v_mov_b64_e32 v[34:35], v[50:51]
	v_mov_b64_e32 v[46:47], v[62:63]
	v_mov_b64_e32 v[42:43], v[58:59]
	v_mov_b64_e32 v[36:37], v[52:53]
	v_mov_b64_e32 v[40:41], v[56:57]
	v_mov_b64_e32 v[44:45], v[60:61]
	v_mov_b64_e32 v[48:49], v[64:65]
	s_branch .LBB0_1087

; #define GAS __attribute__((address_space(1)))
; __device__ __forceinline__ unsigned pk2(float lo, float hi) { return pg8::cvt_pk_bf16(lo, hi); }
; #define INP(k) (*(const float* const __attribute__((address_space(4)))*)(ka + 8 * (k)))
; __device__ __forceinline__ int launder_si(int v) { asm volatile("" : "+s"(v)); return v; }
; __device__ __forceinline__ void phase_norm(Frame& F, int l, int mode) {
;     ...
;     const int gw = launder_si(F.vcu * NWAVES + F.wave), NGW = F.G * NWAVES;
;     GAS bf16* XB = (GAS bf16*)out_; GAS bf16* XS = (GAS bf16*)(ws_ + WS_RKV); GAS bf16* HB = (GAS bf16*)(ws_ + WS_HB);
;     const float* gain = (mode == 0) ? INP(5) + (size_t)l * D : (mode == 1) ? INP(22) + (size_t)l * D : INP(25);
;     if (mode == 0 && gw < BS) {
;         const int j = gw; GAS v2u* o8 = (GAS v2u*)(HB + (size_t)(M + j) * D) + lane;
; #pragma unroll
;         for (int q = 0; q < 8; ++q) { const f32x4 s = *((const GAS f32x4*)(INP(3) + ((size_t)l * BS + j) * D) + lane + 64 * q); v2u w; w.x = pk2(s.x, s.y); w.y = pk2(s.z, s.w); o8[64 * q] = w; }
;     }
;     f32x4 g[4][2];
; #pragma unroll
;     for (int q = 0; q < 4; ++q) { const GAS f32x4* gp = (const GAS f32x4*)(gain + q * 512 + lane * 8); g[q][0] = gp[0]; g[q][1] = gp[1]; }
;     const bool from_in = (mode == 0 && l == 0);
;     const GAS bf16* XR = (mode == 2) ? XS : XB;
;     GAS bf16* XW = (mode == 1 && l == NL - 1) ? XS : XB;
;     f32x4 nf[4][2]; v4u nb[4];
;     ...
;     if (gw < M) NORM_LOAD(gw);
.LBB0_1290:
	s_cmp_lt_i32 s50, 50
	s_cselect_b64 s[0:1], -1, 0
	s_cmp_gt_i32 s51, 49
	s_cselect_b64 s[2:3], -1, 0
	s_and_b64 s[0:1], s[0:1], s[2:3]
	s_and_b64 vcc, exec, s[0:1]
	v_readlane_b32 s16, v254, 12
	s_and_b32 s98, s16, 7
	s_lshl_b32 s98, s98, 8
	s_lshr_b32 s16, s16, 3
	s_add_i32 s16, s16, s98
	v_readlane_b32 s17, v254, 13
	s_cbranch_vccz .LBB0_1298
	v_readlane_b32 s0, v254, 0
	v_readlane_b32 s1, v254, 1
	v_mbcnt_lo_u32_b32 v0, -1, 0
	v_mbcnt_hi_u32_b32 v0, -1, v0
	s_nop 0
	v_writelane_b32 v254, s0, 0
	s_nop 1
	v_writelane_b32 v254, s1, 1
	s_nop 0
	v_readlane_b32 s12, v254, 4
	v_readlane_b32 s13, v254, 5
	v_readlane_b32 s14, v254, 6
	v_readlane_b32 s15, v254, 7
	s_cmpk_gt_i32 s16, 0x43ff
	s_cbranch_scc1 .LBB0_1298
	v_readlane_b32 s2, v254, 0
	v_readlane_b32 s3, v254, 1
	s_add_u32 s4, s14, 0x3d5a0000
	s_load_dwordx2 s[2:3], s[2:3], 0xc8
	s_waitcnt lgkmcnt(0)
	s_addc_u32 s11, s15, 0
	s_ashr_i32 s17, s16, 31
	s_lshl_b64 s[0:1], s[16:17], 12
	v_lshlrev_b32_e32 v0, 3, v0
	s_add_u32 s0, s4, s0
	v_ashrrev_i32_e32 v1, 31, v0
	s_addc_u32 s1, s11, s1
	v_lshlrev_b64 v[32:33], 1, v[0:1]
	v_lshlrev_b64 v[36:37], 2, v[0:1]
	v_lshl_add_u64 v[34:35], s[0:1], 0, v[32:33]
	v_lshl_add_u64 v[38:39], s[2:3], 0, v[36:37]
	s_mov_b64 s[0:1], 0x1800
	s_movk_i32 s10, 0x1000
	v_lshl_add_u64 v[40:41], v[38:39], 0, s[0:1]
	v_add_co_u32_e32 v42, vcc, s10, v38
	s_mov_b64 s[2:3], 0x1000
	s_nop 0
	v_addc_co_u32_e32 v43, vcc, 0, v39, vcc
	v_lshl_add_u64 v[44:45], v[38:39], 0, s[2:3]
	global_load_dwordx4 v[0:3], v[40:41], off offset:16
	global_load_dwordx4 v[4:7], v[42:43], off
	global_load_dwordx4 v[8:11], v[38:39], off offset:2064
	global_load_dwordx4 v[12:15], v[38:39], off offset:2048
	global_load_dwordx4 v[16:19], v[38:39], off offset:16
	global_load_dwordx4 v[20:23], v[38:39], off
	global_load_dwordx4 v[52:55], v[34:35], off offset:2048
	global_load_dwordx4 v[48:51], v[34:35], off offset:3072
	global_load_dwordx4 v[60:63], v[34:35], off
	global_load_dwordx4 v[56:59], v[34:35], off offset:1024
	global_load_dwordx4 v[24:27], v[42:43], off offset:2048
	global_load_dwordx4 v[28:31], v[44:45], off offset:16
	s_mov_b64 s[6:7], 0x43ba0000
	v_lshl_add_u64 v[34:35], s[14:15], 0, v[32:33]
	v_lshl_add_u64 v[80:81], v[34:35], 0, s[6:7]
	s_lshl_b64 s[6:7], s[16:17], 13
	s_add_u32 s12, s12, s6
	s_addc_u32 s13, s13, s7
	s_add_i32 s14, s16, s44
	s_ashr_i32 s15, s14, 31
	s_lshl_b64 s[6:7], s[44:45], 13
	v_lshl_add_u64 v[82:83], s[12:13], 0, v[36:37]
	s_lshl_b64 s[12:13], s[14:15], 12
	s_add_u32 s12, s4, s12
	s_addc_u32 s13, s11, s13
	s_mov_b64 s[8:9], 0x800
	v_lshl_add_u64 v[32:33], s[12:13], 0, v[32:33]
	v_lshl_add_u64 v[84:85], v[32:33], 0, s[8:9]
	s_mov_b32 s5, 0
	v_mov_b32_e32 v134, 0x358637bd
	s_waitcnt vmcnt(0)
	v_mov_b64_e32 v[36:37], v[52:53]
	v_mov_b64_e32 v[32:33], v[48:49]
	v_mov_b64_e32 v[44:45], v[60:61]
	v_mov_b64_e32 v[40:41], v[56:57]
	v_mov_b64_e32 v[34:35], v[50:51]
	v_mov_b64_e32 v[38:39], v[54:55]
	v_mov_b64_e32 v[42:43], v[58:59]
	v_mov_b64_e32 v[46:47], v[62:63]
	s_branch .LBB0_1294
